# P6 q-projection split-K across the idle 128 workgroups (f32 partial hand-off), on top of P1 split
# speedup vs baseline: 1.0279x; 1.0044x over previous
; #define LAS __attribute__((address_space(3)))
; #define REPS(k) for (int rep_ = 0; rep_ < (((RPM) >> (k)) & 1) + 1; ++rep_)
; template <int MAPK>
; __device__ __forceinline__ void transpose_item(const float* W, int K, int N, int ND, bf16_t* WT, const float* g, LAS float* scr, int item, int lane) {
;     const int nblk = ND / 64, kb = item / nblk, nb = item % nblk, k0 = 64 * kb, n0 = 64 * nb;
;     const int c4 = (lane & 15) * 4, kr = lane >> 4;
;     int src = n0 + c4; if (MAPK == 1) src = inmap(src); if (MAPK == 2) src = upmap(src);
;     f32x4 vv[16];
; #pragma unroll
;     for (int i = 0; i < 16; ++i) { const int kk = 4 * i + kr;
;         vv[i] = (f32x4){0.f, 0.f, 0.f, 0.f};
;         if (src >= 0) vv[i] = *(const f32x4*)(W + (size_t)(k0 + kk) * N + src); }
; #pragma unroll
;     for (int i = 0; i < 16; ++i) { const int kk = 4 * i + kr; f32x4 v = vv[i];
;         if (g) v = v * g[k0 + kk];
;         scr[kk * 65 + c4] = v[0]; scr[kk * 65 + c4 + 1] = v[1]; scr[kk * 65 + c4 + 2] = v[2]; scr[kk * 65 + c4 + 3] = v[3]; }
; __global__ void __launch_bounds__(512, 2) hybrid_fwd(Params p) {
;     ...
;     if (PH(0)) REPS(0) { PHB
;         LAS float* scr = (LAS float*)(lds + wave * 16640);
;         const int gw = c * 8 + wave, NGW = G * 8;
;         constexpr int I_IN = 32 * (NWIN / 64), I_OUT = 32 * 32, I_Q = 32 * 8, I_KV = 32 * 16, I_O = 8 * 32, I_UP = 32 * 176, I_DN = 88 * 32;
;         constexpr int I_LAYER = I_IN + I_OUT + I_Q + I_KV + I_O + I_UP + I_DN;
;         for (int it = gw; it < 4 * I_LAYER; it += NGW) {
;             const int l = it / I_LAYER; int r = it % I_LAYER; unsigned char* wl = ws + WS_W + (size_t)l * SZ_LAYER;
;             if (r < I_IN) { transpose_item<1>(p.w_in + (size_t)l * D_ * INC, D_, INC, NWIN, (bf16_t*)(WL + OF_WIN), p.norm_mix + l * D_, scr, r, lane); continue; } r -= I_IN;
.LBB0_19:
	v_readlane_b32 s4, v255, 1
	s_nop 3
	s_cmp_eq_u32 s4, 0x100
	s_cselect_b32 s5, 1, 0
	s_movk_i32 s6, 0x200
	s_cselect_b32 s6, s6, 0x7fffffff
	s_mov_b32 s7, 0
	s_nop 0
	v_writelane_b32 v255, s5, 58
	v_writelane_b32 v255, s7, 59
	v_writelane_b32 v255, s6, 63
	s_cselect_b32 s5, 12, 28
	s_cselect_b32 s6, 13, 29
	s_nop 0
	v_writelane_b32 v255, s5, 56
	v_writelane_b32 v255, s6, 55
	v_writelane_b32 v255, s7, 57
	s_load_dwordx16 s[52:67], s[0:1], 0x0
	s_load_dwordx16 s[12:27], s[0:1], 0x40
	s_andn2_b32 s10, s10, 63
	v_mbcnt_hi_u32_b32 v235, -1, v0
	v_add_u32_e32 v234, s10, v235
	v_mov_b32_e32 v72, v234
	s_waitcnt lgkmcnt(0)
	v_writelane_b32 v255, s12, 4
	s_mov_b64 s[4:5], s[50:51]
	s_nop 0
	v_writelane_b32 v255, s13, 5
	v_writelane_b32 v255, s14, 6
	v_writelane_b32 v255, s15, 7
	v_writelane_b32 v255, s16, 8
	v_writelane_b32 v255, s17, 9
	v_writelane_b32 v255, s18, 10
	v_writelane_b32 v255, s19, 11
	v_writelane_b32 v255, s20, 12
	v_writelane_b32 v255, s21, 13
	v_writelane_b32 v255, s22, 14
	v_writelane_b32 v255, s23, 15
	v_writelane_b32 v255, s24, 16
	v_writelane_b32 v255, s25, 17
	v_writelane_b32 v255, s26, 18
	v_writelane_b32 v255, s27, 19
	s_nop 0
	v_readlane_b32 s26, v255, 0
	v_readlane_b32 s27, v255, 1
	s_lshl_b32 s1, s26, 3
	v_readfirstlane_b32 s0, v72
	s_ashr_i32 s0, s0, 6
	v_and_b32_e32 v73, 63, v72
	s_add_i32 s6, s0, s1
	s_lshl_b32 s8, s27, 3
	s_cmp_gt_i32 s6, 0xc9ff
	v_lshlrev_b32_e32 v74, 2, v73
	s_cbranch_scc1 .LBB0_244
	s_cmp_lg_u64 s[36:37], 0
	s_cselect_b64 s[2:3], -1, 0
	v_writelane_b32 v255, s2, 20
	v_lshlrev_b32_e32 v0, 3, v73
	s_mulk_i32 s0, 0x4100
	v_writelane_b32 v255, s3, 21
	v_lshrrev_b32_e32 v84, 3, v73
	v_readlane_b32 s68, v255, 4
	v_readlane_b32 s76, v255, 12
	v_readlane_b32 s77, v255, 13
	v_readlane_b32 s74, v255, 10
	v_readlane_b32 s75, v255, 11
	s_cmp_lg_u64 s[76:77], 0
	v_readlane_b32 s72, v255, 8
	v_readlane_b32 s73, v255, 9
	s_cselect_b64 s[2:3], -1, 0
	s_cmp_lg_u64 s[74:75], 0
	s_cselect_b64 s[14:15], -1, 0
	s_cmp_lg_u64 s[72:73], 0
	v_and_b32_e32 v0, 56, v0
	s_cselect_b64 s[16:17], -1, 0
	s_add_i32 s0, s0, 0
	v_lshrrev_b32_e32 v76, 4, v73
	v_mul_u32_u24_e32 v2, 0x104, v0
	v_lshlrev_b32_e32 v3, 2, v84
	s_movk_i32 s1, 0x104
	v_add3_u32 v85, s0, v2, v3
	v_or_b32_e32 v2, 4, v76
	v_mov_b32_e32 v3, 0x410
	v_mad_u32_u24 v94, v2, s1, v3
	v_mov_b32_e32 v3, 0xc30
	v_and_b32_e32 v75, 60, v74
	v_mad_u32_u24 v95, v2, s1, v3
	v_mov_b32_e32 v3, 0x1450
	s_add_u32 s7, s4, 0x200000
	v_lshl_add_u32 v82, v75, 2, s0
	v_mad_u32_u24 v96, v2, s1, v3
	v_mov_b32_e32 v3, 0x1c70
	v_readlane_b32 s69, v255, 5
	v_readlane_b32 s70, v255, 6
	v_readlane_b32 s71, v255, 7
	v_readlane_b32 s78, v255, 14
	v_readlane_b32 s79, v255, 15
	v_readlane_b32 s80, v255, 16
	v_readlane_b32 s81, v255, 17
	v_readlane_b32 s82, v255, 18
	v_readlane_b32 s83, v255, 19
	v_writelane_b32 v255, s2, 22
	s_addc_u32 s9, s5, 0
	v_mad_u32_u24 v83, v76, s1, v82
	v_mov_b32_e32 v1, 0
	v_mad_u32_u24 v97, v2, s1, v3
	v_mov_b32_e32 v3, 0x2490
	s_lshl_b32 s0, s6, 2
	v_writelane_b32 v255, s3, 23
	v_or_b32_e32 v86, 8, v84
	v_or_b32_e32 v87, 16, v84
	v_or_b32_e32 v88, 24, v84
	v_or_b32_e32 v89, 32, v84
	v_or_b32_e32 v90, 40, v84
	v_or_b32_e32 v91, 48, v84
	v_or_b32_e32 v92, 56, v84
	v_mul_u32_u24_e32 v93, 0x104, v2
	v_mad_u32_u24 v98, v2, s1, v3
	v_mov_b32_e32 v77, v1
	s_lshl_b32 s28, s6, 6
	s_lshl_b32 s29, s8, 6
	s_lshl_b32 s30, s6, 1
	s_lshl_b32 s31, s8, 1
	s_lshl_b32 s33, s6, 3
	s_lshl_b32 s34, s8, 3
	s_add_i32 s35, s0, 0x3c600
	s_lshl_b32 s95, s8, 2
	s_mov_b32 s96, 0x8000
	s_mov_b32 s97, 0x10000
	s_mov_b32 s10, 0x18000
	s_mov_b32 s11, 0x20000
	s_mov_b32 s85, 0x28000
	s_mov_b32 s86, 0x30000
	s_mov_b32 s87, 0x38000
	s_mov_b32 s2, 0x40000
	s_mov_b32 s3, 0x48000
	s_mov_b32 s12, 0x50000
	s_mov_b32 s13, 0x58000
	s_mov_b32 s93, 0x60000
	s_mov_b32 s94, 0x68000
	s_mov_b32 s84, 0x78000
	v_add_u32_e32 v99, 0x410, v83
	v_add_u32_e32 v100, 0x418, v83
	v_add_u32_e32 v101, 0x820, v83
	v_add_u32_e32 v102, 0x828, v83
	v_add_u32_e32 v103, 0xc30, v83
	v_add_u32_e32 v104, 0xc38, v83
	v_add_u32_e32 v105, 0x1040, v83
	v_add_u32_e32 v106, 0x1048, v83
	v_add_u32_e32 v107, 0x1450, v83
	v_add_u32_e32 v108, 0x1458, v83
	v_add_u32_e32 v109, 0x1860, v83
	v_add_u32_e32 v110, 0x1868, v83
	v_add_u32_e32 v111, 0x1c70, v83
	v_add_u32_e32 v112, 0x1c78, v83
	v_add_u32_e32 v113, 0x2080, v83
	v_add_u32_e32 v114, 0x2088, v83
	v_add_u32_e32 v115, 0x2490, v83
	v_add_u32_e32 v116, 0x2498, v83
	v_add_u32_e32 v117, 0x28a0, v83
	v_add_u32_e32 v118, 0x28a8, v83
	v_add_u32_e32 v119, 0x2cb0, v83
	v_add_u32_e32 v120, 0x2cb8, v83
	v_add_u32_e32 v121, 0x30c0, v83
	v_add_u32_e32 v122, 0x30c8, v83
	v_add_u32_e32 v123, 0x34d0, v83
	v_add_u32_e32 v124, 0x34d8, v83
	v_add_u32_e32 v125, 0x38e0, v83
	v_add_u32_e32 v126, 0x38e8, v83
	v_add_u32_e32 v127, 0x3cf0, v83
	v_add_u32_e32 v128, 0x3cf8, v83
	v_mov_b32_e32 v129, 0x100
	v_mov_b32_e32 v130, 0x400
	v_mov_b32_e32 v131, 0x12140
	v_mov_b32_e32 v132, 0x24280
	v_mov_b32_e32 v133, 0x363c0
	v_mov_b32_e32 v134, 0x48500
	v_mov_b32_e32 v135, 0x5a640
	v_mov_b32_e32 v136, 0x6c780
	v_mov_b32_e32 v137, 0x7e8c0
	v_mov_b32_e32 v138, 0x90a00
	v_mov_b32_e32 v139, 0xa2b40
	v_mov_b32_e32 v140, 0xb4c80
	v_mov_b32_e32 v141, 0xc6dc0
	v_mov_b32_e32 v142, 0xd8f00
	v_mov_b32_e32 v143, 0xeb040
	v_mov_b32_e32 v144, 0xfd180
	v_mov_b32_e32 v145, 0x10f2c0
	v_lshlrev_b32_e32 v78, 1, v0
	s_movk_i32 s88, 0x4850
	s_mov_b32 s89, s6
	s_branch .LBB0_23

; #define PG8_STAGE(bufoff, gbase, voff) do { _Pragma("unroll") for (int _i = 0; _i < 2; ++_i) \
;         __builtin_amdgcn_global_load_lds((const unsigned*)((const char*)(gbase) + (voff)[_i]), (LAS unsigned*)(lds + (bufoff) + ldsw + _i * 8192), 16, 0, 0); } while (0)
; #define PG8_WAIT_V(n) asm volatile("s_waitcnt vmcnt(" #n ")" ::: "memory")
; #define PG8_BAR __builtin_amdgcn_s_barrier()
; template <class Epi, class Sched, bool APERM = false, bool HALFN = false>
; __device__ __forceinline__ void gemm_phase(LAS unsigned char* lds, const int tid_in, const int K, const Sched& S, const Epi& E) {
;     ...
;     for (int i = 0; i < 2; ++i) { int R, C; stage_rc(tid * 16 + i * 8192, R, C); const int Rb = Epi::PERM ? ((R & ~31) + perm32(R & 31)) : R;
;         const int Ra = APERM ? (128 * (R >> 6) + 8 * (R & 15) + ((R >> 4) & 3)) : R;
;         voffA[i] = (unsigned)(Ra * K + C) * 2u; voffB[i] = (unsigned)(Rb * K + C) * 2u; }
;     const size_t kstep = (size_t)(BK * 2);
;     const size_t hstep = (size_t)HALF * K * 2;
;     const size_t hstepA = APERM ? (size_t)4 * K * 2 : hstep;
;     const unsigned ldsw = (unsigned)wid * 1024u;
;     const int aoff = lds_byte(wr * 64 + fr, fq * 8), boff = lds_byte(wc * 32 + fr, fq * 8);
;     ...
;     AB cur, nxt; int ui = 0;
;     if (!S.next(0, cur)) return;
;     f32x4 acc[2][2][4][2];
; #pragma unroll
;     for (int a = 0; a < 2; ++a)
; #pragma unroll
;         for (int b = 0; b < 2; ++b)
; #pragma unroll
;             for (int m = 0; m < 4; ++m)
; #pragma unroll
;                 for (int n = 0; n < 2; ++n) acc[a][b][m][n] = (f32x4){0.f, 0.f, 0.f, 0.f};
;     bf16x8 At[4][2], B0[2][2], B1[2][2];
;     const char* cA = cur.A; const char* cB = cur.B;
;     PG8_STAGE(PG8_SB(0, 0), cB, voffB); PG8_STAGE(PG8_SB(0, 1), cB + hstep, voffB); PG8_STAGE(PG8_SA(0, 0), cA, voffA); PG8_STAGE(PG8_SA(0, 1), cA + hstepA, voffA);
;     if (wr == 1) PG8_BAR;
;     PG8_WAIT_V(2); PG8_BAR;
;     PG8_STAGE(PG8_SB(1, 0), cB + kstep, voffB); PG8_STAGE(PG8_SA(1, 0), cA + kstep, voffA); PG8_STAGE(PG8_SB(1, 1), cB + hstep + kstep, voffB);
;     PG8_WAIT_V(6); PG8_BAR;
;     __device__ __forceinline__ bool next(int i, AB& u) const {
;     ...
;         u.A = (const char*)(ws + WS_HB) + (size_t)(Lx & 31) * 256 * D_ * 2; u.B = (const char*)(ws + WS_W + (size_t)l * SZ_LAYER + OF_WQ) + (size_t)(Lx >> 5) * 128 * D_ * 2; return true;
.LBB0_759:
	s_or_b64 exec, exec, s[0:1]
	s_mov_b32 s29, s73
	s_mov_b32 s26, s22
	v_readlane_b32 s24, v255, 0
	v_mov_b32_e32 v147, v234
	s_waitcnt lgkmcnt(0)
	s_barrier
	s_lshl_b32 s0, s28, 5
	s_mov_b64 s[2:3], s[50:51]
	v_mov_b32_e32 v12, v147
	v_writelane_b32 v255, s28, 42
	s_mov_b32 s1, s73
	v_readfirstlane_b32 s25, v147
	v_readlane_b32 s4, v255, 58
	v_readfirstlane_b32 s12, v12
	v_writelane_b32 v255, s29, 43
	s_nop 1
	s_cmp_eq_u32 s4, 0
	s_cbranch_scc1 .Lp6_orig
	s_lshr_b32 s4, s24, 7
	s_and_b32 s24, s24, 0x7f
	s_nop 0
	v_writelane_b32 v255, s4, 57
	s_branch .Lp6_go
.Lp6_orig:
	s_cmpk_lt_i32 s24, 0x80
	s_cbranch_scc0 .LBB0_781
.Lp6_go:
	v_lshlrev_b32_e32 v0, 4, v12
	v_add_u32_e32 v1, 0x2000, v0
	v_ashrrev_i32_e32 v2, 31, v1
	v_lshrrev_b32_e32 v2, 22, v2
	v_add_u32_e32 v2, v1, v2
	v_ashrrev_i32_e32 v8, 10, v2
	v_mul_i32_i24_e32 v2, 0x400, v8
	v_sub_u32_e32 v1, v1, v2
	v_lshrrev_b32_e32 v2, 4, v1
	v_bitop3_b32 v1, v2, v1, 32 bitop3:0x6c
	v_ashrrev_i32_e32 v2, 31, v1
	v_lshrrev_b32_e32 v2, 26, v2
	v_add_u32_e32 v2, v1, v2
	v_lshlrev_b32_e32 v3, 3, v8
	v_ashrrev_i32_e32 v9, 6, v2
	v_and_b32_e32 v3, -16, v3
	v_add_u32_e32 v3, v9, v3
	v_and_b32_e32 v4, 3, v9
	s_mov_b32 s4, 0xfffe0
	v_lshrrev_b32_e32 v5, 2, v3
	v_lshlrev_b32_e32 v6, 1, v3
	v_and_b32_e32 v2, 0xc0, v2
	v_and_or_b32 v4, v3, s4, v4
	v_and_b32_e32 v5, 4, v5
	v_and_b32_e32 v6, 24, v6
	v_sub_u32_e32 v1, v1, v2
	v_or3_b32 v4, v4, v5, v6
	v_lshlrev_b32_e32 v5, 5, v8
	v_ashrrev_i16_sdwa v1, v238, sext(v1) dst_sel:DWORD dst_unused:UNUSED_PAD src0_sel:DWORD src1_sel:BYTE_0
	v_and_b32_e32 v5, 32, v5
	v_bfe_i32 v10, v1, 0, 16
	v_add_lshl_u32 v1, v5, v10, 1
	v_lshl_add_u32 v64, v4, 12, v1
	v_lshl_add_u32 v66, v3, 12, v1
	v_bfe_i32 v1, v12, 27, 1
	v_lshrrev_b32_e32 v1, 22, v1
	v_add_u32_e32 v1, v0, v1
	v_and_b32_e32 v1, 0xfffffc00, v1
	v_sub_u32_e32 v0, v0, v1
	v_lshrrev_b32_e32 v1, 4, v0
	v_ashrrev_i32_e32 v2, 31, v12
	v_bitop3_b32 v0, v1, v0, 32 bitop3:0x6c
	v_lshrrev_b32_e32 v2, 26, v2
	v_ashrrev_i32_e32 v1, 31, v0
	v_add_u32_e32 v2, v12, v2
	v_lshrrev_b32_e32 v1, 26, v1
	v_ashrrev_i32_e32 v13, 6, v2
	s_ashr_i32 s14, s12, 6
	v_add_u32_e32 v1, v0, v1
	v_lshlrev_b32_e32 v2, 3, v13
	s_ashr_i32 s13, s12, 8
	s_lshl_b32 s27, s14, 10
	v_ashrrev_i32_e32 v11, 6, v1
	v_and_b32_e32 v2, -16, v2
	v_add_u32_e32 v2, v11, v2
	v_and_b32_e32 v3, 3, v11
	s_add_u32 s28, s2, 0x1d600000
	v_and_or_b32 v3, v2, s4, v3
	s_addc_u32 s29, s3, 0
	s_lshl_b32 s4, s24, 20
	s_and_b32 s4, s4, 0x1f00000
	s_add_u32 s6, s28, s4
	s_addc_u32 s7, s29, 0
	v_readlane_b32 s4, v255, 39
	s_add_u32 s4, s2, s4
	s_addc_u32 s5, s3, 0
	s_add_u32 s30, s4, 0x1d00000
	v_lshrrev_b32_e32 v4, 2, v2
	v_lshlrev_b32_e32 v5, 1, v2
	v_and_b32_e32 v1, 0xc0, v1
	s_addc_u32 s31, s5, 0
	s_ashr_i32 s4, s24, 5
	v_and_b32_e32 v4, 4, v4
	v_and_b32_e32 v5, 24, v5
	v_sub_u32_e32 v0, v0, v1
	s_ashr_i32 s5, s4, 31
	v_or3_b32 v3, v3, v4, v5
	v_lshlrev_b32_e32 v4, 5, v13
	v_ashrrev_i16_sdwa v0, v238, sext(v0) dst_sel:DWORD dst_unused:UNUSED_PAD src0_sel:DWORD src1_sel:BYTE_0
	s_lshl_b64 s[8:9], s[4:5], 19
	v_and_b32_e32 v4, 32, v4
	v_bfe_i32 v14, v0, 0, 16
	s_add_u32 s8, s30, s8
	v_add_lshl_u32 v0, v4, v14, 1
	s_addc_u32 s9, s31, s9
	v_readlane_b32 s10, v255, 57
	s_nop 3
	s_lshl_b32 s10, s10, 11
	s_add_u32 s8, s8, s10
	s_addc_u32 s9, s9, 0
	s_add_u32 s6, s6, s10
	s_addc_u32 s7, s7, 0
	s_add_i32 s34, s27, 0
	v_lshl_add_u32 v68, v3, 12, v0
	s_add_i32 m0, s34, 0x10000
	v_lshl_add_u32 v70, v2, 12, v0
	global_load_lds_dwordx4 v68, s[8:9]
	s_add_i32 m0, s34, 0x12000
	s_add_u32 s10, s8, 0x80000
	s_addc_u32 s11, s9, 0
	s_add_i32 s35, s34, 0x14000
	global_load_lds_dwordx4 v64, s[8:9]
	s_mov_b32 m0, s35
	s_add_i32 s38, s34, 0x16000
	global_load_lds_dwordx4 v68, s[10:11]
	s_mov_b32 m0, s38
	s_add_i32 s39, s34, 0x2000
	global_load_lds_dwordx4 v64, s[10:11]
	s_mov_b32 m0, s34
	s_add_u32 s10, s6, 0x80000
	global_load_lds_dwordx4 v70, s[6:7]
	s_mov_b32 m0, s39
	s_addc_u32 s11, s7, 0
	s_add_i32 s44, s34, 0x4000
	global_load_lds_dwordx4 v66, s[6:7]
	s_mov_b32 m0, s44
	s_add_i32 s45, s34, 0x6000
	global_load_lds_dwordx4 v70, s[10:11]
	s_mov_b32 m0, s45
	v_mov_b32_e32 v69, v201
	global_load_lds_dwordx4 v66, s[10:11]
	v_mov_b32_e32 v65, v201
	v_mov_b32_e32 v71, v201
	v_mov_b32_e32 v67, v201
	s_cmp_eq_u32 s13, 1
	v_lshl_add_u64 v[6:7], s[8:9], 0, v[68:69]
	v_lshl_add_u64 v[4:5], s[8:9], 0, v[64:65]
	v_lshl_add_u64 v[0:1], s[6:7], 0, v[70:71]
	s_cselect_b64 s[10:11], -1, 0
	s_cmp_lg_u32 s13, 1
	v_lshl_add_u64 v[2:3], s[6:7], 0, v[66:67]
	s_cbranch_scc1 .LBB0_762
	s_barrier

; #define PG8_STAGE(bufoff, gbase, voff) do { _Pragma("unroll") for (int _i = 0; _i < 2; ++_i) \
;         __builtin_amdgcn_global_load_lds((const unsigned*)((const char*)(gbase) + (voff)[_i]), (LAS unsigned*)(lds + (bufoff) + ldsw + _i * 8192), 16, 0, 0); } while (0)
; #define PG8_LDA(dst, b, h) do { _Pragma("unroll") for (int m = 0; m < 4; ++m) _Pragma("unroll") for (int k = 0; k < 2; ++k) dst[m][k] = *(const LAS bf16x8*)(lds + PG8_SA(b, h) + aoff + m * 2048 + k * 1024); } while (0)
; #define PG8_LDB(dst, b, h) do { _Pragma("unroll") for (int n = 0; n < 2; ++n) _Pragma("unroll") for (int k = 0; k < 2; ++k) dst[n][k] = *(const LAS bf16x8*)(lds + PG8_SB(b, h) + boff + n * 2048 + k * 1024); } while (0)
; #define PG8_MMA(ai, bj, At, Bt) do { __builtin_amdgcn_s_setprio(1); _Pragma("unroll") for (int m = 0; m < 4; ++m) _Pragma("unroll") for (int n = 0; n < 2; ++n) _Pragma("unroll") for (int k = 0; k < 2; ++k) \
;         acc[ai][bj][m][n] = __builtin_amdgcn_mfma_f32_16x16x32_bf16(Bt[n][k], At[m][k], acc[ai][bj][m][n], 0, 0, 0); __builtin_amdgcn_s_setprio(0); } while (0)
; #define PG8_WAIT_V(n) asm volatile("s_waitcnt vmcnt(" #n ")" ::: "memory")
; #define PG8_WAIT_L(n) asm volatile("s_waitcnt lgkmcnt(" #n ")" ::: "memory")
; #define PG8_BAR __builtin_amdgcn_s_barrier()
; #define PG8_SCHED __builtin_amdgcn_sched_barrier(0)
; template <class Epi, class Sched, bool APERM = false, bool HALFN = false>
; __device__ __forceinline__ void gemm_phase(LAS unsigned char* lds, const int tid_in, const int K, const Sched& S, const Epi& E) {
;     ...
;             PG8_LDB(B0, 0, 0); PG8_LDB(B1, 0, 1); PG8_SCHED; PG8_LDA(At, 0, 0); PG8_STAGE(PG8_SA(1, 1), a1 + hstepA, voffA);
;             PG8_WAIT_V(8); PG8_WAIT_L(0); PG8_BAR; PG8_MMA(0, 0, At, B0); if constexpr (!HALFN) PG8_MMA(0, 1, At, B1); PG8_BAR; PG8_SCHED;
;             PG8_LDA(At, 0, 1); PG8_STAGE(PG8_SB(0, 0), b2, voffB); PG8_STAGE(PG8_SB(0, 1), b2 + hstep, voffB); PG8_STAGE(PG8_SA(0, 0), a2, voffA);
;             PG8_WAIT_V(8); PG8_WAIT_L(0); PG8_BAR; PG8_MMA(1, 0, At, B0); if constexpr (!HALFN) PG8_MMA(1, 1, At, B1); PG8_BAR; PG8_SCHED;
;             PG8_LDB(B0, 1, 0); PG8_LDB(B1, 1, 1); PG8_SCHED; PG8_LDA(At, 1, 0); PG8_STAGE(PG8_SA(0, 1), a2 + hstepA, voffA);
;             PG8_WAIT_V(8); PG8_WAIT_L(0); PG8_BAR; PG8_MMA(0, 0, At, B0); if constexpr (!HALFN) PG8_MMA(0, 1, At, B1); PG8_BAR; PG8_SCHED;
.LBB0_766:
	s_add_u32 s20, s18, 0xfff80080
	s_addc_u32 s21, s19, -1
	s_add_i32 s87, 0, 0x10000
	v_add_u32_e32 v95, s87, v99
	ds_read_b128 v[102:105], v95
	ds_read_b128 v[106:109], v95 offset:1024
	ds_read_b128 v[110:113], v95 offset:2048
	ds_read_b128 v[114:117], v95 offset:3072
	v_readlane_b32 s22, v255, 56
	s_nop 1
	s_cmp_eq_u32 s86, s22
	s_cselect_b32 s23, s76, s21
	s_cselect_b32 s22, s77, s20
	s_cselect_b32 s21, s74, s81
	s_cselect_b32 s20, s75, s80
	v_lshl_add_u64 v[96:97], s[18:19], 0, v[92:93]
	s_add_i32 m0, s34, 0xc000
	ds_read_b128 v[118:121], v101
	ds_read_b128 v[122:125], v101 offset:1024
	ds_read_b128 v[126:129], v101 offset:2048
	ds_read_b128 v[130:133], v101 offset:3072
	ds_read_b128 v[134:137], v101 offset:4096
	ds_read_b128 v[138:141], v101 offset:5120
	ds_read_b128 v[142:145], v101 offset:6144
	ds_read_b128 v[148:151], v101 offset:7168
	global_load_lds_dwordx4 v[96:97], off
	v_lshl_add_u64 v[96:97], s[18:19], 0, v[90:91]
	s_add_i32 m0, s34, 0xe000
	s_nop 0
	global_load_lds_dwordx4 v[96:97], off
	s_waitcnt vmcnt(8)
	s_waitcnt lgkmcnt(0)
	s_barrier
	s_setprio 1
	s_waitcnt lgkmcnt(0)
	v_mfma_f32_16x16x32_bf16 v[60:63], v[102:105], v[118:121], v[60:63]
	v_mfma_f32_16x16x32_bf16 v[56:59], v[110:113], v[118:121], v[56:59]
	v_mfma_f32_16x16x32_bf16 v[52:55], v[102:105], v[126:129], v[52:55]
	v_mfma_f32_16x16x32_bf16 v[48:51], v[110:113], v[126:129], v[48:51]
	v_mfma_f32_16x16x32_bf16 v[44:47], v[102:105], v[134:137], v[44:47]
	v_mfma_f32_16x16x32_bf16 v[40:43], v[110:113], v[134:137], v[40:43]
	v_mfma_f32_16x16x32_bf16 v[36:39], v[102:105], v[142:145], v[36:39]
	v_mfma_f32_16x16x32_bf16 v[32:35], v[110:113], v[142:145], v[32:35]
	v_mfma_f32_16x16x32_bf16 v[60:63], v[106:109], v[122:125], v[60:63]
	v_mfma_f32_16x16x32_bf16 v[56:59], v[114:117], v[122:125], v[56:59]
	v_mfma_f32_16x16x32_bf16 v[52:55], v[106:109], v[130:133], v[52:55]
	v_mfma_f32_16x16x32_bf16 v[48:51], v[114:117], v[130:133], v[48:51]
	v_mfma_f32_16x16x32_bf16 v[44:47], v[106:109], v[138:141], v[44:47]
	v_mfma_f32_16x16x32_bf16 v[40:43], v[114:117], v[138:141], v[40:43]
	v_mfma_f32_16x16x32_bf16 v[36:39], v[106:109], v[148:151], v[36:39]
	v_mfma_f32_16x16x32_bf16 v[32:35], v[114:117], v[148:151], v[32:35]
	s_setprio 0
	s_barrier
	s_add_i32 s87, s87, s27
	v_lshl_add_u64 v[96:97], s[20:21], 0, v[68:69]
	s_mov_b32 m0, s87
	ds_read_b128 v[118:121], v101 offset:16384
	ds_read_b128 v[122:125], v101 offset:17408
	ds_read_b128 v[126:129], v101 offset:18432
	ds_read_b128 v[130:133], v101 offset:19456
	ds_read_b128 v[134:137], v101 offset:20480
	ds_read_b128 v[138:141], v101 offset:21504
	ds_read_b128 v[142:145], v101 offset:22528
	ds_read_b128 v[148:151], v101 offset:23552
	global_load_lds_dwordx4 v[96:97], off
	s_add_i32 m0, s87, 0x2000
	s_add_u32 s92, s20, 0x80000
	v_lshl_add_u64 v[152:153], s[20:21], 0, v[64:65]
	s_addc_u32 s93, s21, 0
	global_load_lds_dwordx4 v[152:153], off
	v_lshl_add_u64 v[154:155], s[92:93], 0, v[68:69]
	s_mov_b32 m0, s35
	v_lshl_add_u64 v[156:157], s[22:23], 0, v[66:67]
	global_load_lds_dwordx4 v[154:155], off
	v_lshl_add_u64 v[154:155], s[92:93], 0, v[64:65]
	s_mov_b32 m0, s38
	s_nop 0
	global_load_lds_dwordx4 v[154:155], off
	v_lshl_add_u64 v[154:155], s[22:23], 0, v[70:71]
	s_mov_b32 m0, s34
	s_nop 0
	global_load_lds_dwordx4 v[154:155], off
	s_mov_b32 m0, s39
	s_nop 0
	global_load_lds_dwordx4 v[156:157], off
	s_waitcnt vmcnt(8)
	s_waitcnt lgkmcnt(0)
	s_barrier
	s_setprio 1
	s_waitcnt lgkmcnt(0)
	v_mfma_f32_16x16x32_bf16 v[28:31], v[102:105], v[118:121], v[28:31]
	v_mfma_f32_16x16x32_bf16 v[24:27], v[110:113], v[118:121], v[24:27]
	v_mfma_f32_16x16x32_bf16 v[20:23], v[102:105], v[126:129], v[20:23]
	v_mfma_f32_16x16x32_bf16 v[16:19], v[110:113], v[126:129], v[16:19]
	v_mfma_f32_16x16x32_bf16 v[12:15], v[102:105], v[134:137], v[12:15]
	v_mfma_f32_16x16x32_bf16 v[8:11], v[110:113], v[134:137], v[8:11]
	v_mfma_f32_16x16x32_bf16 v[4:7], v[102:105], v[142:145], v[4:7]
	v_mfma_f32_16x16x32_bf16 v[0:3], v[110:113], v[142:145], v[0:3]
	v_mfma_f32_16x16x32_bf16 v[28:31], v[106:109], v[122:125], v[28:31]
	v_mfma_f32_16x16x32_bf16 v[24:27], v[114:117], v[122:125], v[24:27]
	v_mfma_f32_16x16x32_bf16 v[20:23], v[106:109], v[130:133], v[20:23]
	v_mfma_f32_16x16x32_bf16 v[16:19], v[114:117], v[130:133], v[16:19]
	v_mfma_f32_16x16x32_bf16 v[12:15], v[106:109], v[138:141], v[12:15]
	v_mfma_f32_16x16x32_bf16 v[8:11], v[114:117], v[138:141], v[8:11]
	v_mfma_f32_16x16x32_bf16 v[4:7], v[106:109], v[148:151], v[4:7]
	v_mfma_f32_16x16x32_bf16 v[0:3], v[114:117], v[148:151], v[0:3]
	s_setprio 0
	s_barrier
	s_add_i32 s87, 0, 0x18000
	v_add_u32_e32 v95, s87, v99
	ds_read_b128 v[102:105], v95
	ds_read_b128 v[106:109], v95 offset:1024
	ds_read_b128 v[110:113], v95 offset:2048
	ds_read_b128 v[114:117], v95 offset:3072
	s_add_u32 s22, s22, 0x80000
	s_addc_u32 s23, s23, 0
	s_mov_b32 m0, s44
	v_lshl_add_u64 v[158:159], s[22:23], 0, v[70:71]
	ds_read_b128 v[118:121], v101 offset:32768
	ds_read_b128 v[122:125], v101 offset:33792
	ds_read_b128 v[126:129], v101 offset:34816
	ds_read_b128 v[130:133], v101 offset:35840
	ds_read_b128 v[134:137], v101 offset:36864
	ds_read_b128 v[138:141], v101 offset:37888
	ds_read_b128 v[142:145], v101 offset:38912
	ds_read_b128 v[148:151], v101 offset:39936
	global_load_lds_dwordx4 v[158:159], off
	v_lshl_add_u64 v[158:159], s[22:23], 0, v[66:67]
	s_mov_b32 m0, s45
	s_nop 0
	global_load_lds_dwordx4 v[158:159], off
	s_waitcnt vmcnt(8)
	s_waitcnt lgkmcnt(0)
	s_barrier
; #define PG8_STAGE(bufoff, gbase, voff) do { _Pragma("unroll") for (int _i = 0; _i < 2; ++_i) \
;         __builtin_amdgcn_global_load_lds((const unsigned*)((const char*)(gbase) + (voff)[_i]), (LAS unsigned*)(lds + (bufoff) + ldsw + _i * 8192), 16, 0, 0); } while (0)
; #define PG8_LDA(dst, b, h) do { _Pragma("unroll") for (int m = 0; m < 4; ++m) _Pragma("unroll") for (int k = 0; k < 2; ++k) dst[m][k] = *(const LAS bf16x8*)(lds + PG8_SA(b, h) + aoff + m * 2048 + k * 1024); } while (0)
; #define PG8_MMA(ai, bj, At, Bt) do { __builtin_amdgcn_s_setprio(1); _Pragma("unroll") for (int m = 0; m < 4; ++m) _Pragma("unroll") for (int n = 0; n < 2; ++n) _Pragma("unroll") for (int k = 0; k < 2; ++k) \
;         acc[ai][bj][m][n] = __builtin_amdgcn_mfma_f32_16x16x32_bf16(Bt[n][k], At[m][k], acc[ai][bj][m][n], 0, 0, 0); __builtin_amdgcn_s_setprio(0); } while (0)
; #define PG8_WAIT_V(n) asm volatile("s_waitcnt vmcnt(" #n ")" ::: "memory")
; #define PG8_WAIT_L(n) asm volatile("s_waitcnt lgkmcnt(" #n ")" ::: "memory")
; #define PG8_BAR __builtin_amdgcn_s_barrier()
; #define PG8_SCHED __builtin_amdgcn_sched_barrier(0)
;     __device__ __forceinline__ CU2 full(int i) const { const int Lx = i * G + c; CU2 u; tile_order(Lx, 33, 44, u.pm, u.pn); return u; }
; template <class Epi, class Sched, bool APERM = false, bool HALFN = false>
; __device__ __forceinline__ void gemm_phase(LAS unsigned char* lds, const int tid_in, const int K, const Sched& S, const Epi& E) {
;     ...
;             PG8_WAIT_V(8); PG8_WAIT_L(0); PG8_BAR; PG8_MMA(0, 0, At, B0); if constexpr (!HALFN) PG8_MMA(0, 1, At, B1); PG8_BAR; PG8_SCHED;
;             PG8_LDA(At, 1, 1); PG8_STAGE(PG8_SB(1, 0), b3, voffB); PG8_STAGE(PG8_SB(1, 1), b3 + hstep, voffB); PG8_STAGE(PG8_SA(1, 0), a3, voffA);
;             PG8_WAIT_V(8); PG8_WAIT_L(0); PG8_BAR; PG8_MMA(1, 0, At, B0); if constexpr (!HALFN) PG8_MMA(1, 1, At, B1); PG8_BAR; PG8_SCHED;
;         }
;         if (wr == 0) PG8_BAR;
;         { const Unit fu = S.full(ui); E(acc, fu, wr, wc, fr, fq); }
	s_setprio 1
	s_waitcnt lgkmcnt(0)
	v_mfma_f32_16x16x32_bf16 v[60:63], v[102:105], v[118:121], v[60:63]
	v_mfma_f32_16x16x32_bf16 v[56:59], v[110:113], v[118:121], v[56:59]
	v_mfma_f32_16x16x32_bf16 v[52:55], v[102:105], v[126:129], v[52:55]
	v_mfma_f32_16x16x32_bf16 v[48:51], v[110:113], v[126:129], v[48:51]
	v_mfma_f32_16x16x32_bf16 v[44:47], v[102:105], v[134:137], v[44:47]
	v_mfma_f32_16x16x32_bf16 v[40:43], v[110:113], v[134:137], v[40:43]
	v_mfma_f32_16x16x32_bf16 v[36:39], v[102:105], v[142:145], v[36:39]
	v_mfma_f32_16x16x32_bf16 v[32:35], v[110:113], v[142:145], v[32:35]
	v_mfma_f32_16x16x32_bf16 v[60:63], v[106:109], v[122:125], v[60:63]
	v_mfma_f32_16x16x32_bf16 v[56:59], v[114:117], v[122:125], v[56:59]
	v_mfma_f32_16x16x32_bf16 v[52:55], v[106:109], v[130:133], v[52:55]
	v_mfma_f32_16x16x32_bf16 v[48:51], v[114:117], v[130:133], v[48:51]
	v_mfma_f32_16x16x32_bf16 v[44:47], v[106:109], v[138:141], v[44:47]
	v_mfma_f32_16x16x32_bf16 v[40:43], v[114:117], v[138:141], v[40:43]
	v_mfma_f32_16x16x32_bf16 v[36:39], v[106:109], v[148:151], v[36:39]
	v_mfma_f32_16x16x32_bf16 v[32:35], v[114:117], v[148:151], v[32:35]
	s_setprio 0
	s_barrier
	s_add_i32 s22, s87, s27
	v_lshl_add_u64 v[96:97], v[96:97], 0, s[78:79]
	s_mov_b32 m0, s22
	ds_read_b128 v[118:121], v101 offset:49152
	ds_read_b128 v[122:125], v101 offset:50176
	ds_read_b128 v[126:129], v101 offset:51200
	ds_read_b128 v[130:133], v101 offset:52224
	ds_read_b128 v[134:137], v101 offset:53248
	ds_read_b128 v[138:141], v101 offset:54272
	ds_read_b128 v[142:145], v101 offset:55296
	ds_read_b128 v[148:151], v101 offset:56320
	global_load_lds_dwordx4 v[96:97], off
	s_add_i32 m0, s22, 0x2000
	s_add_u32 s20, s20, 0x80080
	v_lshl_add_u64 v[96:97], v[152:153], 0, s[78:79]
	s_addc_u32 s21, s21, 0
	global_load_lds_dwordx4 v[96:97], off
	v_lshl_add_u64 v[96:97], s[20:21], 0, v[68:69]
	s_mov_b32 m0, s57
	s_nop 0
	global_load_lds_dwordx4 v[96:97], off
	v_lshl_add_u64 v[96:97], s[20:21], 0, v[64:65]
	s_mov_b32 m0, s70
	s_nop 0
	global_load_lds_dwordx4 v[96:97], off
	v_lshl_add_u64 v[96:97], v[154:155], 0, s[78:79]
	s_mov_b32 m0, s52
	s_nop 0
	global_load_lds_dwordx4 v[96:97], off
	v_lshl_add_u64 v[96:97], v[156:157], 0, s[78:79]
	s_mov_b32 m0, s53
	s_nop 0
	global_load_lds_dwordx4 v[96:97], off
	s_waitcnt vmcnt(8)
	s_waitcnt lgkmcnt(0)
	s_barrier
	s_setprio 1
	s_waitcnt lgkmcnt(0)
	v_mfma_f32_16x16x32_bf16 v[28:31], v[102:105], v[118:121], v[28:31]
	v_mfma_f32_16x16x32_bf16 v[24:27], v[110:113], v[118:121], v[24:27]
	v_mfma_f32_16x16x32_bf16 v[20:23], v[102:105], v[126:129], v[20:23]
	v_mfma_f32_16x16x32_bf16 v[16:19], v[110:113], v[126:129], v[16:19]
	v_mfma_f32_16x16x32_bf16 v[12:15], v[102:105], v[134:137], v[12:15]
	v_mfma_f32_16x16x32_bf16 v[8:11], v[110:113], v[134:137], v[8:11]
	v_mfma_f32_16x16x32_bf16 v[4:7], v[102:105], v[142:145], v[4:7]
	v_mfma_f32_16x16x32_bf16 v[0:3], v[110:113], v[142:145], v[0:3]
	v_mfma_f32_16x16x32_bf16 v[28:31], v[106:109], v[122:125], v[28:31]
	v_mfma_f32_16x16x32_bf16 v[24:27], v[114:117], v[122:125], v[24:27]
	v_mfma_f32_16x16x32_bf16 v[20:23], v[106:109], v[130:133], v[20:23]
	v_mfma_f32_16x16x32_bf16 v[16:19], v[114:117], v[130:133], v[16:19]
	v_mfma_f32_16x16x32_bf16 v[12:15], v[106:109], v[138:141], v[12:15]
	v_mfma_f32_16x16x32_bf16 v[8:11], v[114:117], v[138:141], v[8:11]
	v_mfma_f32_16x16x32_bf16 v[4:7], v[106:109], v[148:151], v[4:7]
	v_mfma_f32_16x16x32_bf16 v[0:3], v[114:117], v[148:151], v[0:3]
	s_setprio 0
	s_barrier
	s_add_i32 s86, s86, 2
	s_add_u32 s80, s80, 0x100
	s_addc_u32 s81, s81, 0
	s_add_u32 s18, s18, 0x100
	s_addc_u32 s19, s19, 0
	v_readlane_b32 s20, v255, 55
	s_nop 1
	s_cmp_gt_u32 s86, s20
	s_cbranch_scc0 .LBB0_766
	s_and_b64 vcc, exec, s[12:13]
	s_cbranch_vccz .LBB0_769
	s_barrier
.LBB0_769:
	v_readlane_b32 s18, v255, 58
	v_readlane_b32 s19, v255, 57
	s_nop 3
	s_cmp_eq_u32 s18, 0
	s_cbranch_scc1 .Lp6_epi
	s_cmp_eq_u32 s19, 0
	s_cbranch_scc1 .Lp6_consumer
	s_lshl_b32 s18, s24, 17
	s_lshl_b32 s19, s25, 8
	s_and_b32 s19, s19, 0x1c000
	s_add_i32 s18, s18, s19
	s_add_u32 s20, s50, 0x27600000
	s_addc_u32 s21, s51, 0
	s_add_u32 s20, s20, s18
	s_addc_u32 s21, s21, 0
	v_and_b32_e32 v96, 63, v147
	v_lshlrev_b32_e32 v96, 4, v96
	v_mov_b32_e32 v97, 0
	s_mov_b64 s[22:23], 0x1000
	v_lshl_add_u64 v[96:97], s[20:21], 0, v[96:97]
	global_store_dwordx4 v[96:97], v[0:3], off sc1
	global_store_dwordx4 v[96:97], v[4:7], off offset:1024 sc1
	global_store_dwordx4 v[96:97], v[8:11], off offset:2048 sc1
	global_store_dwordx4 v[96:97], v[12:15], off offset:3072 sc1
	v_lshl_add_u64 v[96:97], v[96:97], 0, s[22:23]
	global_store_dwordx4 v[96:97], v[16:19], off sc1
	global_store_dwordx4 v[96:97], v[20:23], off offset:1024 sc1
	global_store_dwordx4 v[96:97], v[24:27], off offset:2048 sc1
	global_store_dwordx4 v[96:97], v[28:31], off offset:3072 sc1
	v_lshl_add_u64 v[96:97], v[96:97], 0, s[22:23]
	global_store_dwordx4 v[96:97], v[32:35], off sc1
	global_store_dwordx4 v[96:97], v[36:39], off offset:1024 sc1
	global_store_dwordx4 v[96:97], v[40:43], off offset:2048 sc1
	global_store_dwordx4 v[96:97], v[44:47], off offset:3072 sc1
	v_lshl_add_u64 v[96:97], v[96:97], 0, s[22:23]
	global_store_dwordx4 v[96:97], v[48:51], off sc1
	global_store_dwordx4 v[96:97], v[52:55], off offset:1024 sc1
	global_store_dwordx4 v[96:97], v[56:59], off offset:2048 sc1
	global_store_dwordx4 v[96:97], v[60:63], off offset:3072 sc1
	s_waitcnt vmcnt(0)
	s_barrier
	v_cmp_eq_u32_e32 vcc, 0, v147
	s_and_saveexec_b64 s[22:23], vcc
	s_cbranch_execz .Lp6_pub_done
	s_lshl_b32 s18, s24, 2
	s_add_u32 s20, s50, 0x3e00
	s_addc_u32 s21, s51, 0
	s_add_u32 s20, s20, s18
	s_addc_u32 s21, s21, 0
	v_mov_b32_e32 v96, s20
	v_mov_b32_e32 v97, s21
	global_atomic_add v[96:97], v238, off
; #define PG8_BAR __builtin_amdgcn_s_barrier()
;     __device__ __forceinline__ CU2 full(int i) const { const int Lx = i * G + c; CU2 u; tile_order(Lx, 33, 44, u.pm, u.pn); return u; }
; template <class Epi, class Sched, bool APERM = false, bool HALFN = false>
; __device__ __forceinline__ void gemm_phase(LAS unsigned char* lds, const int tid_in, const int K, const Sched& S, const Epi& E) {
;     ...
;         if (wr == 0) PG8_BAR;
;         { const Unit fu = S.full(ui); E(acc, fu, wr, wc, fr, fq); }
; __global__ void __launch_bounds__(512, 2) hybrid_fwd(Params p) {
;     ...
;             if (tid == 0) { unsigned* cw_ = (unsigned*)ws + 3840 + 32 * l + (c & 31); unsigned sp_ = 0;
;                 while (__hip_atomic_load(cw_, __ATOMIC_RELAXED, __HIP_MEMORY_SCOPE_AGENT) < 4u) { __builtin_amdgcn_s_sleep(2); if (++sp_ > (1u << 22)) break; }
;                 __builtin_amdgcn_fence(__ATOMIC_ACQUIRE, "agent"); asm volatile("s_waitcnt vmcnt(0)" ::: "memory"); }
.Lp6_pub_done:
	s_or_b64 exec, exec, s[22:23]
	v_readlane_b32 s22, v255, 1
	s_waitcnt vmcnt(0)
	s_nop 2
	s_branch .LBB0_781
.Lp6_consumer:
	v_cmp_eq_u32_e32 vcc, 0, v147
	s_and_saveexec_b64 s[22:23], vcc
	s_cbranch_execz .Lp6_wait_done
	s_lshl_b32 s18, s24, 2
	s_add_u32 s20, s50, 0x3e00
	s_addc_u32 s21, s51, 0
	s_add_u32 s20, s20, s18
	s_addc_u32 s21, s21, 0
	v_mov_b32_e32 v96, s20
	v_mov_b32_e32 v97, s21
	v_readlane_b32 s19, v255, 42
	s_mov_b32 s18, 0x200000
	s_nop 1
	s_add_i32 s19, s19, 1
.Lp6_spin:
	global_load_dword v98, v[96:97], off sc1
	s_waitcnt vmcnt(0)
	v_readfirstlane_b32 s20, v98
	s_nop 3
	s_cmp_ge_u32 s20, s19
	s_cbranch_scc1 .Lp6_spin_done
	s_add_i32 s18, s18, -1
	s_cmp_eq_u32 s18, 0
	s_cbranch_scc1 .Lp6_spin_done
	s_sleep 2
	s_branch .Lp6_spin
.Lp6_spin_done:
	buffer_inv sc1
	s_waitcnt vmcnt(0)
.Lp6_wait_done:
	s_or_b64 exec, exec, s[22:23]
	s_waitcnt vmcnt(0) lgkmcnt(0)
	s_barrier
	s_lshl_b32 s18, s24, 17
	s_lshl_b32 s19, s25, 8
	s_and_b32 s19, s19, 0x1c000
	s_add_i32 s18, s18, s19
	s_add_u32 s20, s50, 0x27600000
	s_addc_u32 s21, s51, 0
	s_add_u32 s20, s20, s18
	s_addc_u32 s21, s21, 0
	v_and_b32_e32 v96, 63, v147
	v_lshlrev_b32_e32 v96, 4, v96
	v_mov_b32_e32 v97, 0
	s_mov_b64 s[22:23], 0x1000
	v_lshl_add_u64 v[96:97], s[20:21], 0, v[96:97]
	global_load_dwordx4 v[102:105], v[96:97], off sc1
	global_load_dwordx4 v[106:109], v[96:97], off offset:1024 sc1
	global_load_dwordx4 v[110:113], v[96:97], off offset:2048 sc1
	global_load_dwordx4 v[114:117], v[96:97], off offset:3072 sc1
	v_lshl_add_u64 v[96:97], v[96:97], 0, s[22:23]
	global_load_dwordx4 v[118:121], v[96:97], off sc1
	global_load_dwordx4 v[122:125], v[96:97], off offset:1024 sc1
	global_load_dwordx4 v[126:129], v[96:97], off offset:2048 sc1
	global_load_dwordx4 v[130:133], v[96:97], off offset:3072 sc1
	v_lshl_add_u64 v[96:97], v[96:97], 0, s[22:23]
	s_waitcnt vmcnt(0)
	v_add_f32_e32 v0, v0, v102
	v_add_f32_e32 v1, v1, v103
	v_add_f32_e32 v2, v2, v104
	v_add_f32_e32 v3, v3, v105
	v_add_f32_e32 v4, v4, v106
	v_add_f32_e32 v5, v5, v107
	v_add_f32_e32 v6, v6, v108
	v_add_f32_e32 v7, v7, v109
	v_add_f32_e32 v8, v8, v110
	v_add_f32_e32 v9, v9, v111
	v_add_f32_e32 v10, v10, v112
	v_add_f32_e32 v11, v11, v113
	v_add_f32_e32 v12, v12, v114
	v_add_f32_e32 v13, v13, v115
	v_add_f32_e32 v14, v14, v116
	v_add_f32_e32 v15, v15, v117
	v_add_f32_e32 v16, v16, v118
	v_add_f32_e32 v17, v17, v119
	v_add_f32_e32 v18, v18, v120
	v_add_f32_e32 v19, v19, v121
	v_add_f32_e32 v20, v20, v122
	v_add_f32_e32 v21, v21, v123
	v_add_f32_e32 v22, v22, v124
	v_add_f32_e32 v23, v23, v125
	v_add_f32_e32 v24, v24, v126
	v_add_f32_e32 v25, v25, v127
	v_add_f32_e32 v26, v26, v128
	v_add_f32_e32 v27, v27, v129
	v_add_f32_e32 v28, v28, v130
	v_add_f32_e32 v29, v29, v131
	v_add_f32_e32 v30, v30, v132
	v_add_f32_e32 v31, v31, v133
	global_load_dwordx4 v[102:105], v[96:97], off sc1
	global_load_dwordx4 v[106:109], v[96:97], off offset:1024 sc1
	global_load_dwordx4 v[110:113], v[96:97], off offset:2048 sc1
	global_load_dwordx4 v[114:117], v[96:97], off offset:3072 sc1
	v_lshl_add_u64 v[96:97], v[96:97], 0, s[22:23]
	global_load_dwordx4 v[118:121], v[96:97], off sc1
	global_load_dwordx4 v[122:125], v[96:97], off offset:1024 sc1
	global_load_dwordx4 v[126:129], v[96:97], off offset:2048 sc1
	global_load_dwordx4 v[130:133], v[96:97], off offset:3072 sc1
	v_lshl_add_u64 v[96:97], v[96:97], 0, s[22:23]
	s_waitcnt vmcnt(0)
	v_add_f32_e32 v32, v32, v102
	v_add_f32_e32 v33, v33, v103
	v_add_f32_e32 v34, v34, v104
	v_add_f32_e32 v35, v35, v105
	v_add_f32_e32 v36, v36, v106
	v_add_f32_e32 v37, v37, v107
	v_add_f32_e32 v38, v38, v108
	v_add_f32_e32 v39, v39, v109
	v_add_f32_e32 v40, v40, v110
	v_add_f32_e32 v41, v41, v111
	v_add_f32_e32 v42, v42, v112
	v_add_f32_e32 v43, v43, v113
	v_add_f32_e32 v44, v44, v114
	v_add_f32_e32 v45, v45, v115
	v_add_f32_e32 v46, v46, v116
	v_add_f32_e32 v47, v47, v117
	v_add_f32_e32 v48, v48, v118
	v_add_f32_e32 v49, v49, v119
	v_add_f32_e32 v50, v50, v120
	v_add_f32_e32 v51, v51, v121
	v_add_f32_e32 v52, v52, v122
	v_add_f32_e32 v53, v53, v123
	v_add_f32_e32 v54, v54, v124
	v_add_f32_e32 v55, v55, v125
	v_add_f32_e32 v56, v56, v126
	v_add_f32_e32 v57, v57, v127
	v_add_f32_e32 v58, v58, v128
	v_add_f32_e32 v59, v59, v129
	v_add_f32_e32 v60, v60, v130
	v_add_f32_e32 v61, v61, v131
	v_add_f32_e32 v62, v62, v132
	v_add_f32_e32 v63, v63, v133
